# scoring loop: canonicalize-copy + relu pairs folded into one v_max (16 fewer VALU ops per iteration)
# speedup vs baseline: 1.0047x; 1.0028x over previous
.LBB0_1094:
	s_and_b32 s44, 1, s33
	s_cselect_b32 s45, 0, 0x9000
	s_cmp_lt_u32 s43, s34
	v_add_u32_e32 v131, s45, v107
	v_lshl_add_u64 v[150:151], s[30:31], 0, v[136:137]
	s_cbranch_scc0 .LBB0_1101
	ds_read_b128 v[0:3], v131
	ds_read_b128 v[16:19], v131 offset:32
	s_add_i32 s45, s43, 1
	s_cmp_ge_u32 s45, s34
	s_waitcnt lgkmcnt(1)
	v_mfma_f32_32x32x16_bf16 v[0:15], v[48:51], v[0:3], 0
	s_waitcnt lgkmcnt(0)
	v_mfma_f32_32x32x16_bf16 v[0:15], v[52:55], v[16:19], v[0:15]
	ds_read_b128 v[16:19], v131 offset:64
	ds_read_b128 v[20:23], v131 offset:4608
	ds_read_b128 v[208:211], v131 offset:4640
	ds_read_b128 v[24:27], v131 offset:9216
	ds_read_b128 v[212:215], v131 offset:9248
	ds_read_b128 v[28:31], v131 offset:96
	ds_read_b128 v[216:219], v131 offset:13824
	ds_read_b128 v[220:223], v131 offset:13856
	ds_read_b128 v[224:227], v131 offset:4672
	ds_read_b128 v[228:231], v131 offset:4704
	ds_read_b128 v[232:235], v131 offset:9280
	ds_read_b128 v[236:239], v131 offset:9312
	ds_read_b128 v[240:243], v131 offset:13888
	ds_read_b128 v[244:247], v131 offset:13920
	s_waitcnt lgkmcnt(13)
	v_mfma_f32_32x32x16_bf16 v[0:15], v[56:59], v[16:19], v[0:15]
	s_waitcnt lgkmcnt(12)
	v_mfma_f32_32x32x16_bf16 v[32:47], v[48:51], v[20:23], 0
	s_waitcnt lgkmcnt(8)
	v_mfma_f32_32x32x16_bf16 v[0:15], v[60:63], v[28:31], v[0:15]
	v_mfma_f32_32x32x16_bf16 v[32:47], v[52:55], v[208:211], v[32:47]
	s_nop 10
	v_max_f32_e32 v4, 0, v4
	v_max_f32_e32 v5, 0, v5
	v_max_f32_e32 v0, 0, v0
	v_max_f32_e32 v12, 0, v12
	v_max_f32_e32 v1, 0, v1
	v_max_f32_e32 v13, 0, v13
	v_pk_mul_f32 v[4:5], v[68:69], v[4:5]
	v_max_f32_e32 v8, 0, v8
	v_max_f32_e32 v9, 0, v9
	v_pk_mul_f32 v[12:13], v[76:77], v[12:13]
	v_pk_fma_f32 v[0:1], v[64:65], v[0:1], v[4:5]
	s_waitcnt lgkmcnt(5)
	v_mfma_f32_32x32x16_bf16 v[32:47], v[56:59], v[224:227], v[32:47]
	v_fma_f32 v4, v72, v8, v12
	v_fma_f32 v5, v73, v9, v13
	v_add_f32_e32 v0, 0, v0
	v_add_f32_e32 v8, v1, v0
	v_add_f32_e32 v0, 0, v4
	v_add_f32_e32 v9, v5, v0
	v_max_f32_e32 v0, 0, v2
	v_max_f32_e32 v2, 0, v6
	v_max_f32_e32 v4, 0, v10
	v_max_f32_e32 v6, 0, v14
	v_max_f32_e32 v1, 0, v3
	v_max_f32_e32 v3, 0, v7
	v_pk_mul_f32 v[2:3], v[70:71], v[2:3]
	s_waitcnt lgkmcnt(4)
	v_mfma_f32_32x32x16_bf16 v[32:47], v[60:63], v[228:231], v[32:47]
	v_fma_f32 v0, v66, v0, v2
	v_fma_f32 v1, v67, v1, v3
	v_add_f32_e32 v0, v0, v8
	v_add_f32_e32 v133, v1, v0
	v_max_f32_e32 v5, 0, v11
	v_max_f32_e32 v7, 0, v15
	v_pk_mul_f32 v[0:1], v[78:79], v[6:7]
	s_nop 2
	v_pk_fma_f32 v[0:1], v[74:75], v[4:5], v[0:1]
	v_mfma_f32_32x32x16_bf16 v[16:31], v[48:51], v[24:27], 0
	v_add_f32_e32 v0, v0, v9
	v_add_f32_e32 v135, v1, v0
	v_max_f32_e32 v32, 0, v32
	v_max_f32_e32 v36, 0, v36
	v_mul_f32_e32 v36, v68, v36
	v_mfma_f32_32x32x16_bf16 v[0:15], v[48:51], v[216:219], 0
	v_max_f32_e32 v37, 0, v37
	v_fmac_f32_e32 v36, v64, v32
	v_max_f32_e32 v33, 0, v33
	v_mul_f32_e32 v37, v69, v37
	v_add_f32_e32 v32, 0, v36
	v_max_f32_e32 v36, 0, v40
	v_fmac_f32_e32 v37, v65, v33
	v_max_f32_e32 v40, 0, v44
	v_add_f32_e32 v32, v37, v32
	v_mul_f32_e32 v40, v76, v40
	v_max_f32_e32 v37, 0, v45
	v_fmac_f32_e32 v40, v72, v36
	v_max_f32_e32 v33, 0, v41
	v_mul_f32_e32 v37, v77, v37
	v_add_f32_e32 v36, 0, v40
	v_fmac_f32_e32 v37, v73, v33
	v_add_f32_e32 v33, v37, v36
	v_mfma_f32_32x32x16_bf16 v[16:31], v[52:55], v[212:215], v[16:31]
	v_max_f32_e32 v36, 0, v38
	v_max_f32_e32 v34, 0, v34
	v_mul_f32_e32 v36, v70, v36
	v_fmac_f32_e32 v36, v66, v34
	v_add_f32_e32 v32, v36, v32
	v_mfma_f32_32x32x16_bf16 v[0:15], v[52:55], v[220:223], v[0:15]
	v_max_f32_e32 v36, 0, v46
	v_max_f32_e32 v34, 0, v42
	v_mul_f32_e32 v36, v78, v36
	v_fmac_f32_e32 v36, v74, v34
	v_add_f32_e32 v34, v36, v33
	v_max_f32_e32 v33, 0, v35
	s_waitcnt lgkmcnt(3)
	v_mfma_f32_32x32x16_bf16 v[16:31], v[56:59], v[232:235], v[16:31]
	v_max_f32_e32 v35, 0, v39
	v_mul_f32_e32 v35, v71, v35
	v_fmac_f32_e32 v35, v67, v33
	v_add_f32_e32 v33, v35, v32
	s_waitcnt lgkmcnt(1)
	v_mfma_f32_32x32x16_bf16 v[0:15], v[56:59], v[240:243], v[0:15]
	v_max_f32_e32 v35, 0, v47
	v_max_f32_e32 v32, 0, v43
	v_mul_f32_e32 v35, v79, v35
	v_and_b32_e32 v36, 64, v206
	v_fmac_f32_e32 v35, v75, v32
	v_xor_b32_e32 v32, 32, v206
	v_add_u32_e32 v36, 64, v36
	v_cmp_lt_i32_e32 vcc, v32, v36
	v_mfma_f32_32x32x16_bf16 v[16:31], v[60:63], v[236:239], v[16:31]
	v_cndmask_b32_e64 v208, v133, v135, s[0:1]
	v_cndmask_b32_e32 v32, v206, v32, vcc
	v_lshlrev_b32_e32 v32, 2, v32
	v_add_f32_e32 v34, v35, v34
	ds_bpermute_b32 v36, v32, v208
	v_cndmask_b32_e64 v35, v33, v34, s[0:1]
	ds_bpermute_b32 v35, v32, v35
	s_waitcnt lgkmcnt(2)
	v_mfma_f32_32x32x16_bf16 v[0:15], v[60:63], v[244:247], v[0:15]
	v_cndmask_b32_e64 v37, v135, v133, s[0:1]
	s_waitcnt lgkmcnt(1)
	v_add_f32_e32 v36, v37, v36
	global_store_dword v[150:151], v36, off offset:-512
	s_cbranch_scc1 .LBB0_1097
	v_cndmask_b32_e64 v33, v34, v33, s[0:1]
	s_waitcnt lgkmcnt(0)
	v_add_f32_e32 v33, v33, v35
	global_store_dword v[150:151], v33, off offset:-384
.LBB0_1097:
	v_max_f32_e32 v20, 0, v20
	v_max_f32_e32 v16, 0, v16
	v_mul_f32_e32 v20, v68, v20
	v_max_f32_e32 v21, 0, v21
	v_fmac_f32_e32 v20, v64, v16
	v_max_f32_e32 v17, 0, v17
	v_mul_f32_e32 v21, v69, v21
	v_add_f32_e32 v16, 0, v20
	v_max_f32_e32 v20, 0, v24
	v_fmac_f32_e32 v21, v65, v17
	v_max_f32_e32 v24, 0, v28
	v_add_f32_e32 v16, v21, v16
	v_mul_f32_e32 v24, v76, v24
	v_max_f32_e32 v21, 0, v29
	v_fmac_f32_e32 v24, v72, v20
	v_max_f32_e32 v17, 0, v25
	v_mul_f32_e32 v21, v77, v21
	v_add_f32_e32 v20, 0, v24
	v_fmac_f32_e32 v21, v73, v17
	v_add_f32_e32 v17, v21, v20
	v_max_f32_e32 v20, 0, v22
	v_max_f32_e32 v18, 0, v18
	v_mul_f32_e32 v20, v70, v20
	v_fmac_f32_e32 v20, v66, v18
	v_add_f32_e32 v16, v20, v16
	v_max_f32_e32 v20, 0, v30
	v_max_f32_e32 v18, 0, v26
	v_mul_f32_e32 v20, v78, v20
	v_fmac_f32_e32 v20, v74, v18
	v_max_f32_e32 v18, 0, v19
	v_max_f32_e32 v19, 0, v23
	v_mul_f32_e32 v19, v71, v19
	v_fmac_f32_e32 v19, v67, v18
	v_add_f32_e32 v16, v19, v16
	v_max_f32_e32 v19, 0, v31
	v_max_f32_e32 v18, 0, v27
	v_mul_f32_e32 v19, v79, v19
	v_add_f32_e32 v17, v20, v17
	v_fmac_f32_e32 v19, v75, v18
	v_add_f32_e32 v17, v19, v17
	v_cndmask_b32_e64 v18, v16, v17, s[0:1]
	ds_bpermute_b32 v18, v32, v18
	s_add_i32 s45, s43, 2
	s_cmp_ge_u32 s45, s34
	s_cbranch_scc1 .LBB0_1099
	v_cndmask_b32_e64 v16, v17, v16, s[0:1]
	s_waitcnt lgkmcnt(0)
	v_add_f32_e32 v16, v16, v18
	global_store_dword v[150:151], v16, off offset:-256
.LBB0_1099:
	v_max_f32_e32 v4, 0, v4
	v_max_f32_e32 v0, 0, v0
	v_mul_f32_e32 v4, v68, v4
	v_max_f32_e32 v5, 0, v5
	v_fmac_f32_e32 v4, v64, v0
	v_max_f32_e32 v1, 0, v1
	v_mul_f32_e32 v5, v69, v5
	v_add_f32_e32 v0, 0, v4
	v_max_f32_e32 v4, 0, v8
	v_fmac_f32_e32 v5, v65, v1
	v_max_f32_e32 v8, 0, v12
	v_add_f32_e32 v0, v5, v0
	v_mul_f32_e32 v8, v76, v8
	v_max_f32_e32 v5, 0, v13
	v_fmac_f32_e32 v8, v72, v4
	v_max_f32_e32 v1, 0, v9
	v_mul_f32_e32 v5, v77, v5
	v_add_f32_e32 v4, 0, v8
	v_fmac_f32_e32 v5, v73, v1
	v_add_f32_e32 v1, v5, v4
	v_max_f32_e32 v4, 0, v6
	v_max_f32_e32 v2, 0, v2
	v_mul_f32_e32 v4, v70, v4
	v_fmac_f32_e32 v4, v66, v2
	v_add_f32_e32 v0, v4, v0
	v_max_f32_e32 v4, 0, v14
	v_max_f32_e32 v2, 0, v10
	v_mul_f32_e32 v4, v78, v4
	v_fmac_f32_e32 v4, v74, v2
	v_max_f32_e32 v2, 0, v3
	v_max_f32_e32 v3, 0, v7
	v_mul_f32_e32 v3, v71, v3
	v_fmac_f32_e32 v3, v67, v2
	v_add_f32_e32 v0, v3, v0
	v_max_f32_e32 v3, 0, v15
	v_max_f32_e32 v2, 0, v11
	v_mul_f32_e32 v3, v79, v3
	v_add_f32_e32 v1, v4, v1
	v_fmac_f32_e32 v3, v75, v2
	v_add_f32_e32 v1, v3, v1
	v_cndmask_b32_e64 v2, v0, v1, s[0:1]
	ds_bpermute_b32 v2, v32, v2
	s_add_i32 s45, s43, 3
	s_cmp_ge_u32 s45, s34
	s_cbranch_scc1 .LBB0_1101
	v_cndmask_b32_e64 v0, v1, v0, s[0:1]
	s_waitcnt lgkmcnt(0)
	v_add_f32_e32 v0, v0, v2
	global_store_dword v[150:151], v0, off offset:-128
.LBB0_1101:
	s_add_i32 s45, s43, 4
	s_cmp_ge_u32 s45, s34
	s_cbranch_scc1 .LBB0_1108
	s_waitcnt lgkmcnt(0)
	ds_read_b128 v[0:3], v131 offset:18432
	ds_read_b128 v[16:19], v131 offset:18464
	s_add_i32 s45, s43, 5
	s_cmp_ge_u32 s45, s34
	s_waitcnt lgkmcnt(1)
	v_mfma_f32_32x32x16_bf16 v[0:15], v[48:51], v[0:3], 0
	s_waitcnt lgkmcnt(0)
	v_mfma_f32_32x32x16_bf16 v[0:15], v[52:55], v[16:19], v[0:15]
	ds_read_b128 v[16:19], v131 offset:18496
	ds_read_b128 v[20:23], v131 offset:23040
	ds_read_b128 v[208:211], v131 offset:23072
	ds_read_b128 v[24:27], v131 offset:27648
	ds_read_b128 v[212:215], v131 offset:27680
	ds_read_b128 v[28:31], v131 offset:18528
	ds_read_b128 v[216:219], v131 offset:32256
	ds_read_b128 v[220:223], v131 offset:32288
	ds_read_b128 v[224:227], v131 offset:23104
	ds_read_b128 v[228:231], v131 offset:23136
	ds_read_b128 v[232:235], v131 offset:27712
	ds_read_b128 v[236:239], v131 offset:27744
	ds_read_b128 v[240:243], v131 offset:32320
	ds_read_b128 v[244:247], v131 offset:32352
	s_waitcnt lgkmcnt(13)
	v_mfma_f32_32x32x16_bf16 v[0:15], v[56:59], v[16:19], v[0:15]
	s_waitcnt lgkmcnt(12)
	v_mfma_f32_32x32x16_bf16 v[32:47], v[48:51], v[20:23], 0
	s_waitcnt lgkmcnt(8)
	v_mfma_f32_32x32x16_bf16 v[0:15], v[60:63], v[28:31], v[0:15]
	v_mfma_f32_32x32x16_bf16 v[32:47], v[52:55], v[208:211], v[32:47]
	s_nop 10
	v_max_f32_e32 v4, 0, v4
	v_max_f32_e32 v5, 0, v5
	v_max_f32_e32 v0, 0, v0
	v_max_f32_e32 v12, 0, v12
	v_max_f32_e32 v1, 0, v1
	v_max_f32_e32 v13, 0, v13
	v_pk_mul_f32 v[4:5], v[68:69], v[4:5]
	v_max_f32_e32 v8, 0, v8
	v_max_f32_e32 v9, 0, v9
	v_pk_mul_f32 v[12:13], v[76:77], v[12:13]
	v_pk_fma_f32 v[0:1], v[64:65], v[0:1], v[4:5]
	s_waitcnt lgkmcnt(5)
	v_mfma_f32_32x32x16_bf16 v[32:47], v[56:59], v[224:227], v[32:47]
	v_fma_f32 v4, v72, v8, v12
	v_fma_f32 v5, v73, v9, v13
	v_add_f32_e32 v0, 0, v0
	v_add_f32_e32 v8, v1, v0
	v_add_f32_e32 v0, 0, v4
	v_add_f32_e32 v9, v5, v0
	v_max_f32_e32 v0, 0, v2
	v_max_f32_e32 v2, 0, v6
	v_max_f32_e32 v4, 0, v10
	v_max_f32_e32 v6, 0, v14
	v_max_f32_e32 v1, 0, v3
	v_max_f32_e32 v3, 0, v7
	v_pk_mul_f32 v[2:3], v[70:71], v[2:3]
	s_waitcnt lgkmcnt(4)
	v_mfma_f32_32x32x16_bf16 v[32:47], v[60:63], v[228:231], v[32:47]
	v_fma_f32 v0, v66, v0, v2
	v_fma_f32 v1, v67, v1, v3
	v_add_f32_e32 v0, v0, v8
	v_add_f32_e32 v131, v1, v0
	v_max_f32_e32 v5, 0, v11
	v_max_f32_e32 v7, 0, v15
	v_pk_mul_f32 v[0:1], v[78:79], v[6:7]
	s_nop 2
	v_pk_fma_f32 v[0:1], v[74:75], v[4:5], v[0:1]
	v_mfma_f32_32x32x16_bf16 v[16:31], v[48:51], v[24:27], 0
	v_add_f32_e32 v0, v0, v9
	v_add_f32_e32 v133, v1, v0
	v_max_f32_e32 v32, 0, v32
	v_max_f32_e32 v36, 0, v36
	v_mul_f32_e32 v36, v68, v36
	v_mfma_f32_32x32x16_bf16 v[0:15], v[48:51], v[216:219], 0
	v_max_f32_e32 v37, 0, v37
	v_fmac_f32_e32 v36, v64, v32
	v_max_f32_e32 v33, 0, v33
	v_mul_f32_e32 v37, v69, v37
	v_add_f32_e32 v32, 0, v36
	v_max_f32_e32 v36, 0, v40
	v_fmac_f32_e32 v37, v65, v33
	v_max_f32_e32 v40, 0, v44
	v_add_f32_e32 v32, v37, v32
	v_mul_f32_e32 v40, v76, v40
	v_max_f32_e32 v37, 0, v45
	v_fmac_f32_e32 v40, v72, v36
	v_max_f32_e32 v33, 0, v41
	v_mul_f32_e32 v37, v77, v37
	v_add_f32_e32 v36, 0, v40
	v_fmac_f32_e32 v37, v73, v33
	v_add_f32_e32 v33, v37, v36
	v_mfma_f32_32x32x16_bf16 v[16:31], v[52:55], v[212:215], v[16:31]
	v_max_f32_e32 v36, 0, v38
	v_max_f32_e32 v34, 0, v34
	v_mul_f32_e32 v36, v70, v36
	v_fmac_f32_e32 v36, v66, v34
	v_add_f32_e32 v32, v36, v32
	v_mfma_f32_32x32x16_bf16 v[0:15], v[52:55], v[220:223], v[0:15]
	v_max_f32_e32 v36, 0, v46
	v_max_f32_e32 v34, 0, v42
	v_mul_f32_e32 v36, v78, v36
	v_fmac_f32_e32 v36, v74, v34
	v_add_f32_e32 v34, v36, v33
	v_max_f32_e32 v33, 0, v35
	s_waitcnt lgkmcnt(3)
	v_mfma_f32_32x32x16_bf16 v[16:31], v[56:59], v[232:235], v[16:31]
	v_max_f32_e32 v35, 0, v39
	v_mul_f32_e32 v35, v71, v35
	v_fmac_f32_e32 v35, v67, v33
	v_add_f32_e32 v33, v35, v32
	s_waitcnt lgkmcnt(1)
	v_mfma_f32_32x32x16_bf16 v[0:15], v[56:59], v[240:243], v[0:15]
	v_max_f32_e32 v35, 0, v47
	v_max_f32_e32 v32, 0, v43
	v_mul_f32_e32 v35, v79, v35
	v_and_b32_e32 v36, 64, v206
	v_fmac_f32_e32 v35, v75, v32
	v_xor_b32_e32 v32, 32, v206
	v_add_u32_e32 v36, 64, v36
	v_cmp_lt_i32_e32 vcc, v32, v36
	v_mfma_f32_32x32x16_bf16 v[16:31], v[60:63], v[236:239], v[16:31]
	v_cndmask_b32_e64 v135, v131, v133, s[0:1]
	v_cndmask_b32_e32 v32, v206, v32, vcc
	v_lshlrev_b32_e32 v32, 2, v32
	v_add_f32_e32 v34, v35, v34
	ds_bpermute_b32 v36, v32, v135
	v_cndmask_b32_e64 v35, v33, v34, s[0:1]
	ds_bpermute_b32 v35, v32, v35
	s_waitcnt lgkmcnt(2)
	v_mfma_f32_32x32x16_bf16 v[0:15], v[60:63], v[244:247], v[0:15]
	v_cndmask_b32_e64 v37, v133, v131, s[0:1]
	s_waitcnt lgkmcnt(1)
	v_add_f32_e32 v36, v37, v36
	global_store_dword v[150:151], v36, off
	s_cbranch_scc1 .LBB0_1104
	v_cndmask_b32_e64 v33, v34, v33, s[0:1]
	s_waitcnt lgkmcnt(0)
	v_add_f32_e32 v33, v33, v35
	global_store_dword v[150:151], v33, off offset:128
.LBB0_1104:
	v_max_f32_e32 v20, 0, v20
	v_max_f32_e32 v16, 0, v16
	v_mul_f32_e32 v20, v68, v20
	v_max_f32_e32 v21, 0, v21
	v_fmac_f32_e32 v20, v64, v16
	v_max_f32_e32 v17, 0, v17
	v_mul_f32_e32 v21, v69, v21
	v_add_f32_e32 v16, 0, v20
	v_max_f32_e32 v20, 0, v24
	v_fmac_f32_e32 v21, v65, v17
	v_max_f32_e32 v24, 0, v28
	v_add_f32_e32 v16, v21, v16
	v_mul_f32_e32 v24, v76, v24
	v_max_f32_e32 v21, 0, v29
	v_fmac_f32_e32 v24, v72, v20
	v_max_f32_e32 v17, 0, v25
	v_mul_f32_e32 v21, v77, v21
	v_add_f32_e32 v20, 0, v24
	v_fmac_f32_e32 v21, v73, v17
	v_add_f32_e32 v17, v21, v20
	v_max_f32_e32 v20, 0, v22
	v_max_f32_e32 v18, 0, v18
	v_mul_f32_e32 v20, v70, v20
	v_fmac_f32_e32 v20, v66, v18
	v_add_f32_e32 v16, v20, v16
	v_max_f32_e32 v20, 0, v30
	v_max_f32_e32 v18, 0, v26
	v_mul_f32_e32 v20, v78, v20
	v_fmac_f32_e32 v20, v74, v18
	v_max_f32_e32 v18, 0, v19
	v_max_f32_e32 v19, 0, v23
	v_mul_f32_e32 v19, v71, v19
	v_fmac_f32_e32 v19, v67, v18
	v_add_f32_e32 v16, v19, v16
	v_max_f32_e32 v19, 0, v31
	v_max_f32_e32 v18, 0, v27
	v_mul_f32_e32 v19, v79, v19
	v_add_f32_e32 v17, v20, v17
	v_fmac_f32_e32 v19, v75, v18
	v_add_f32_e32 v17, v19, v17
	v_cndmask_b32_e64 v18, v16, v17, s[0:1]
	ds_bpermute_b32 v18, v32, v18
	s_add_i32 s45, s43, 6
	s_cmp_ge_u32 s45, s34
	s_cbranch_scc1 .LBB0_1106
	v_cndmask_b32_e64 v16, v17, v16, s[0:1]
	s_waitcnt lgkmcnt(0)
	v_add_f32_e32 v16, v16, v18
	global_store_dword v[150:151], v16, off offset:256
.LBB0_1106:
	v_max_f32_e32 v4, 0, v4
	v_max_f32_e32 v0, 0, v0
	v_mul_f32_e32 v4, v68, v4
	v_max_f32_e32 v5, 0, v5
	v_fmac_f32_e32 v4, v64, v0
	v_max_f32_e32 v1, 0, v1
	v_mul_f32_e32 v5, v69, v5
	v_add_f32_e32 v0, 0, v4
	v_max_f32_e32 v4, 0, v8
	v_fmac_f32_e32 v5, v65, v1
	v_max_f32_e32 v8, 0, v12
	v_add_f32_e32 v0, v5, v0
	v_mul_f32_e32 v8, v76, v8
	v_max_f32_e32 v5, 0, v13
	v_fmac_f32_e32 v8, v72, v4
	v_max_f32_e32 v1, 0, v9
	v_mul_f32_e32 v5, v77, v5
	v_add_f32_e32 v4, 0, v8
	v_fmac_f32_e32 v5, v73, v1
	v_add_f32_e32 v1, v5, v4
	v_max_f32_e32 v4, 0, v6
	v_max_f32_e32 v2, 0, v2
	v_mul_f32_e32 v4, v70, v4
	v_fmac_f32_e32 v4, v66, v2
	v_add_f32_e32 v0, v4, v0
	v_max_f32_e32 v4, 0, v14
	v_max_f32_e32 v2, 0, v10
	v_mul_f32_e32 v4, v78, v4
	v_fmac_f32_e32 v4, v74, v2
	v_max_f32_e32 v2, 0, v3
	v_max_f32_e32 v3, 0, v7
	v_mul_f32_e32 v3, v71, v3
	v_fmac_f32_e32 v3, v67, v2
	v_add_f32_e32 v0, v3, v0
	v_max_f32_e32 v3, 0, v15
	v_max_f32_e32 v2, 0, v11
	v_mul_f32_e32 v3, v79, v3
	v_add_f32_e32 v1, v4, v1
	v_fmac_f32_e32 v3, v75, v2
	v_add_f32_e32 v1, v3, v1
	v_cndmask_b32_e64 v2, v0, v1, s[0:1]
	ds_bpermute_b32 v2, v32, v2
	s_add_i32 s45, s43, 7
	s_cmp_ge_u32 s45, s34
	s_cbranch_scc1 .LBB0_1108
	v_cndmask_b32_e64 v0, v1, v0, s[0:1]
	s_waitcnt lgkmcnt(0)
	v_add_f32_e32 v0, v0, v2
	global_store_dword v[150:151], v0, off offset:384
